# C + P3 scoring loop: row-block MFMA chains back to back, first block's relu/weight epilogue issued under the second chain
# baseline (speedup 1.0000x reference)
; #define LAS __attribute__((address_space(3)))
; __device__ __forceinline__ void idx_epi(const f32x16& acc, const hp2_t (&wv)[2][4], LAS unsigned char* dst  ) {
;     const hp2_t zero2 = (hp2_t){(_Float16)0.f, (_Float16)0.f};
; #pragma unroll
;     for (int e = 0; e < 2; ++e) { hp2_t sum;
; #pragma unroll
;         for (int i = 0; i < 4; ++i) { hp2_t r = __builtin_bit_cast(hp2_t, __builtin_amdgcn_cvt_pkrtz(acc[8 * e + 2 * i], acc[8 * e + 2 * i + 1])); r = __builtin_elementwise_max(r, zero2);
;             sum = i == 0 ? r * wv[e][0] : __builtin_elementwise_fma(r, wv[e][i], sum); }
;         *(LAS _Float16*)(dst + e * 8192) = sum[0] + sum[1]; }
; }
; __device__ __forceinline__ void idx_scores8(const Params& p, LAS unsigned char* buf, int b, int c, int s8, int pw, int lane, int nw) {
;     ...
;     for (int ct = pw; ct < nct; ct += nw) {
;         const int cn = (ct + nw < nct) ? ct + nw : ct;
;         bf16x8 bnx[4];
; #pragma unroll
;         for (int s = 0; s < 4; ++s) bnx[s] = *(const bf16x8*)(kbase + (size_t)cn * 2048 + 256 * s);
;         const int s0 = ct * 32; const int hf = (s0 >= SP) ? 1 : 0;
;         LAS unsigned char* dst = rowq + (s0 - hf * SP + r) * 4 + 2 * hf;
;         f32x16 accA, accB;
; #pragma unroll
;         for (int i = 0; i < 16; ++i) { accA[i] = 0.f; accB[i] = 0.f; }
; #pragma unroll
;         for (int s = 0; s < 4; ++s) accA = __builtin_amdgcn_mfma_f32_32x32x16_bf16(af[0][s], bcur[s], accA, 0, 0, 0);
; #pragma unroll
;         for (int s = 0; s < 4; ++s) accB = __builtin_amdgcn_mfma_f32_32x32x16_bf16(af[1][s], bcur[s], accB, 0, 0, 0);
;         idx_epi(accA, wv[0], dst);
;         idx_epi(accB, wv[1], dst + 4 * 8192);
; #pragma unroll
;         for (int s = 0; s < 4; ++s) bcur[s] = bnx[s];
;     }
.LBB0_3692:
	s_waitcnt vmcnt(0)
	v_mfma_f32_32x32x16_bf16 v[0:15], v[48:51], v[16:19], 0
	s_add_i32 s10, s5, 4
	s_cmp_lt_u32 s10, s0
	s_cselect_b32 s92, s10, s5
	s_lshl_b64 s[6:7], s[92:93], 12
	v_lshl_add_u64 v[136:137], v[92:93], 0, s[6:7]
	v_mfma_f32_32x32x16_bf16 v[0:15], v[52:55], v[72:75], v[0:15]
	s_cmp_lt_u32 s4, s1
	s_cselect_b32 s6, 0, s1
	s_cselect_b32 s7, 0, 2
	s_lshl_b32 s6, s6, 2
	s_addk_i32 s4, 0x80
	s_sub_i32 s6, s7, s6
	v_mfma_f32_32x32x16_bf16 v[0:15], v[56:59], v[68:71], v[0:15]
	s_mov_b32 s5, s10
	s_cmp_ge_u32 s10, s0
	v_add_u32_e32 v140, s6, v131
	v_add_u32_e32 v131, 0x200, v131
	v_mfma_f32_32x32x16_bf16 v[0:15], v[60:63], v[64:67], v[0:15]
	v_mfma_f32_32x32x16_bf16 v[16:31], v[32:35], v[16:19], 0
	v_mfma_f32_32x32x16_bf16 v[16:31], v[36:39], v[72:75], v[16:31]
	global_load_dwordx4 v[72:75], v[136:137], off
	v_mfma_f32_32x32x16_bf16 v[16:31], v[40:43], v[68:71], v[16:31]
	global_load_dwordx4 v[68:71], v[136:137], off offset:512
	global_load_dwordx4 v[132:135], v[136:137], off offset:1024
	s_nop 0
	global_load_dwordx4 v[136:139], v[136:137], off offset:1536
	v_mfma_f32_32x32x16_bf16 v[16:31], v[44:47], v[64:67], v[16:31]
	s_nop 2
	v_cvt_pkrtz_f16_f32 v0, v0, v1
	v_cvt_pkrtz_f16_f32 v1, v2, v3
	v_cvt_pkrtz_f16_f32 v3, v6, v7
	v_cvt_pkrtz_f16_f32 v7, v8, v9
	v_cvt_pkrtz_f16_f32 v2, v4, v5
	v_cvt_pkrtz_f16_f32 v4, v14, v15
	v_cvt_pkrtz_f16_f32 v6, v10, v11
	v_cvt_pkrtz_f16_f32 v5, v12, v13
	v_pk_max_f16 v0, v0, 0
	v_pk_max_f16 v7, v7, 0
	v_pk_max_f16 v1, v1, 0
	v_pk_max_f16 v6, v6, 0
	v_pk_max_f16 v2, v2, 0
	v_pk_max_f16 v5, v5, 0
	v_pk_max_f16 v3, v3, 0
	v_pk_max_f16 v4, v4, 0
	v_pk_mul_f16 v0, v89, v0
	v_pk_mul_f16 v7, v127, v7
	v_pk_fma_f16 v0, v1, v125, v0
	v_pk_fma_f16 v1, v6, v129, v7
	v_pk_fma_f16 v0, v2, v124, v0
	v_pk_fma_f16 v1, v5, v128, v1
	v_pk_fma_f16 v0, v3, v126, v0
	v_pk_fma_f16 v1, v4, v130, v1
	v_add_f16_sdwa v0, v0, v0 dst_sel:DWORD dst_unused:UNUSED_PAD src0_sel:DWORD src1_sel:WORD_1
	v_add_f16_sdwa v1, v1, v1 dst_sel:DWORD dst_unused:UNUSED_PAD src0_sel:DWORD src1_sel:WORD_1
	v_cvt_pkrtz_f16_f32 v16, v16, v17
	v_cvt_pkrtz_f16_f32 v17, v18, v19
	v_cvt_pkrtz_f16_f32 v19, v22, v23
	v_cvt_pkrtz_f16_f32 v23, v24, v25
	v_cvt_pkrtz_f16_f32 v18, v20, v21
	v_cvt_pkrtz_f16_f32 v22, v26, v27
	v_cvt_pkrtz_f16_f32 v21, v28, v29
	v_cvt_pkrtz_f16_f32 v20, v30, v31
	v_pk_max_f16 v8, v16, 0
	v_pk_max_f16 v9, v17, 0
	v_pk_max_f16 v15, v23, 0
	v_pk_max_f16 v10, v18, 0
	v_pk_max_f16 v11, v19, 0
	v_pk_max_f16 v14, v22, 0
	v_pk_max_f16 v13, v21, 0
	v_pk_max_f16 v12, v20, 0
	v_pk_mul_f16 v8, v116, v8
	v_pk_mul_f16 v15, v120, v15
	v_pk_fma_f16 v8, v9, v118, v8
	v_pk_fma_f16 v9, v14, v122, v15
	v_pk_fma_f16 v6, v10, v117, v8
	v_pk_fma_f16 v7, v13, v121, v9
	v_pk_fma_f16 v2, v11, v119, v6
	v_pk_fma_f16 v5, v12, v123, v7
	s_waitcnt vmcnt(3)
	v_mov_b64_e32 v[16:17], v[72:73]
	v_mov_b64_e32 v[18:19], v[74:75]
	v_add_f16_sdwa v2, v2, v2 dst_sel:DWORD dst_unused:UNUSED_PAD src0_sel:DWORD src1_sel:WORD_1
	v_add_f16_sdwa v3, v5, v5 dst_sel:DWORD dst_unused:UNUSED_PAD src0_sel:DWORD src1_sel:WORD_1
	ds_write_b16 v140, v2
	ds_write_b16 v140, v3 offset:8192
	ds_write_b16 v140, v0 offset:32768
	ds_write_b16 v140, v1 offset:40960
	s_waitcnt vmcnt(2)
	v_mov_b64_e32 v[74:75], v[70:71]
	v_mov_b64_e32 v[72:73], v[68:69]
	s_waitcnt vmcnt(1)
	v_mov_b64_e32 v[68:69], v[132:133]
	s_waitcnt vmcnt(0)
	v_mov_b64_e32 v[64:65], v[136:137]
	v_mov_b64_e32 v[70:71], v[134:135]
	v_mov_b64_e32 v[66:67], v[138:139]
	s_cbranch_scc0 .LBB0_3692
